# GEMM K-loops without s_setprio (load segments are VALU-free), re-measure
# speedup vs baseline: 1.0044x; 1.0004x over previous
;     __device__ __forceinline__ void stage_rs(const Unit& u, int tid, int wid) const { stage_rs_lds(SS, rsl, u, tid, wid); }
;     __device__ __forceinline__ void stage_rs(const Unit& u, int tid, int wid) const { stage_rs_lds(SS, rsl, u, tid, wid); }
; #define PG8_STAGE(bufoff, gbase, voff) do { _Pragma("unroll") for (int _i = 0; _i < 2; ++_i) \
;         __builtin_amdgcn_global_load_lds((const unsigned*)((const char*)(gbase) + (voff)[_i]), (PG8_LAS unsigned*)(lds + (bufoff) + ldsw + _i * 8192), 16, 0, 0); } while (0)
; #define PG8_LDA(dst, b, h) do { _Pragma("unroll") for (int m = 0; m < 4; ++m) _Pragma("unroll") for (int k = 0; k < 2; ++k) dst[m][k] = *(const PG8_LAS bf16x8*)(lds + PG8_SA(b, h) + aoff + m * 2048 + k * 1024); } while (0)
; #define PG8_LDB(dst, b, h) do { _Pragma("unroll") for (int n = 0; n < 2; ++n) _Pragma("unroll") for (int k = 0; k < 2; ++k) dst[n][k] = *(const PG8_LAS bf16x8*)(lds + PG8_SB(b, h) + boff + n * 2048 + k * 1024); } while (0)
; #define PG8_WAIT_V(n) asm volatile("s_waitcnt vmcnt(" #n ")" ::: "memory")
; template <class Epi, class Sched, bool ALIGN_EPI = false, bool SP2 = false>
; __device__ __forceinline__ void gemm_phase(PG8_LAS unsigned char* lds, const Gemm g, const Sched& S, const Epi& E, const int tid) {
;     ...
;             const bool last = (t == nt - 2);
;             if constexpr (Epi::RS_LDS) { if (t == nt - 4) E.stage_rs(cur, tid, wid); }
;             if constexpr (Epi::PREFETCH) { if (t >= nt - 8) E.prefetch(cur, lds, tid, wid, (t - (nt - 8)) >> 1); }
;             const char* a1 = cA + (size_t)(t + 1) * kstep;
;             const char* a2 = last ? nA : cA + (size_t)(t + 2) * kstep; const char* b2 = last ? nB : cB + (size_t)(t + 2) * kstep;
;             const char* a3 = a2 + kstep; const char* b3 = b2 + kstep;
;             if (last && has_next) S.a_ready(nxt);
;             if constexpr (SP2) {
;             PG8_LDB(B0, 0, 0); PG8_LDB(B1, 0, 1); PG8_SCHED; PG8_LDA(At, 0, 0); PG8_STAGE(PG8_SA(1, 1), a1 + hstep, voffA);
;             PG8_WAIT_V(8); PG8_WAIT_L(0); PG8_BAR; PG8_MMA(0, 0, At, B0); PG8_MMA(0, 1, At, B1); PG8_BAR; PG8_SCHED;
;             PG8_LDA(At, 0, 1); PG8_STAGE(PG8_SB(0, 0), b2, voffB); PG8_STAGE(PG8_SB(0, 1), b2 + hstep, voffB); PG8_STAGE(PG8_SA(0, 0), a2, voffA);
;             PG8_WAIT_V(8); PG8_WAIT_L(0); PG8_BAR; PG8_MMA(1, 0, At, B0); PG8_MMA(1, 1, At, B1); PG8_BAR; PG8_SCHED;
.LBB0_87:
	s_add_u32 s38, s22, s68
	s_addc_u32 s39, s23, s69
	s_add_u32 s38, s38, 0x100
	s_addc_u32 s39, s39, 0
	s_add_u32 s94, s38, 0x3ff80
	s_addc_u32 s95, s39, 0
	s_add_u32 s50, s89, s68
	s_addc_u32 s51, s90, s69
	s_add_i32 s92, 0, 0x10000
	s_cmpk_eq_i32 s68, 0x700
	s_cselect_b32 s73, s15, s39
	s_cselect_b32 s72, s86, s38
	s_cselect_b32 s71, s87, s51
	s_cselect_b32 s70, s88, s50
	s_add_i32 s38, 0, 0x14000
	ds_read_b128 v[170:173], v150
	ds_read_b128 v[174:177], v150 offset:1024
	ds_read_b128 v[178:181], v150 offset:2048
	ds_read_b128 v[182:185], v150 offset:3072
	ds_read_b128 v[186:189], v150 offset:16384
	ds_read_b128 v[190:193], v150 offset:17408
	ds_read_b128 v[206:209], v150 offset:18432
	ds_read_b128 v[210:213], v150 offset:19456
	s_add_i32 m0, s76, 0xc000
	ds_read_b128 v[214:217], v167
	ds_read_b128 v[218:221], v167 offset:1024
	ds_read_b128 v[222:225], v167 offset:2048
	ds_read_b128 v[226:229], v167 offset:3072
	ds_read_b128 v[230:233], v167 offset:4096
	ds_read_b128 v[234:237], v167 offset:5120
	ds_read_b128 v[238:241], v167 offset:6144
	ds_read_b128 v[242:245], v167 offset:7168
	global_load_lds_dwordx4 v138, s[94:95]
	s_add_i32 m0, s76, 0xe000
	s_nop 0
	global_load_lds_dwordx4 v140, s[94:95]
	s_waitcnt vmcnt(8)
	s_waitcnt lgkmcnt(0)
	s_barrier
	v_mfma_f32_16x16x32_bf16 v[126:129], v[170:173], v[214:217], v[126:129]
	v_mfma_f32_16x16x32_bf16 v[122:125], v[178:181], v[214:217], v[122:125]
	v_mfma_f32_16x16x32_bf16 v[110:113], v[170:173], v[222:225], v[110:113]
	v_mfma_f32_16x16x32_bf16 v[106:109], v[178:181], v[222:225], v[106:109]
	v_mfma_f32_16x16x32_bf16 v[94:97], v[170:173], v[230:233], v[94:97]
	v_mfma_f32_16x16x32_bf16 v[90:93], v[178:181], v[230:233], v[90:93]
	v_mfma_f32_16x16x32_bf16 v[78:81], v[170:173], v[238:241], v[78:81]
	v_mfma_f32_16x16x32_bf16 v[74:77], v[178:181], v[238:241], v[74:77]
	v_mfma_f32_16x16x32_bf16 v[126:129], v[174:177], v[218:221], v[126:129]
	v_mfma_f32_16x16x32_bf16 v[122:125], v[182:185], v[218:221], v[122:125]
	v_mfma_f32_16x16x32_bf16 v[110:113], v[174:177], v[226:229], v[110:113]
	v_mfma_f32_16x16x32_bf16 v[106:109], v[182:185], v[226:229], v[106:109]
	v_mfma_f32_16x16x32_bf16 v[94:97], v[174:177], v[234:237], v[94:97]
	v_mfma_f32_16x16x32_bf16 v[90:93], v[182:185], v[234:237], v[90:93]
	v_mfma_f32_16x16x32_bf16 v[78:81], v[174:177], v[242:245], v[78:81]
	v_mfma_f32_16x16x32_bf16 v[74:77], v[182:185], v[242:245], v[74:77]
	v_mfma_f32_16x16x32_bf16 v[118:121], v[186:189], v[214:217], v[118:121]
	v_mfma_f32_16x16x32_bf16 v[114:117], v[206:209], v[214:217], v[114:117]
	v_mfma_f32_16x16x32_bf16 v[102:105], v[186:189], v[222:225], v[102:105]
	v_mfma_f32_16x16x32_bf16 v[98:101], v[206:209], v[222:225], v[98:101]
	v_mfma_f32_16x16x32_bf16 v[86:89], v[186:189], v[230:233], v[86:89]
	v_mfma_f32_16x16x32_bf16 v[82:85], v[206:209], v[230:233], v[82:85]
	v_mfma_f32_16x16x32_bf16 v[70:73], v[186:189], v[238:241], v[70:73]
	v_mfma_f32_16x16x32_bf16 v[66:69], v[206:209], v[238:241], v[66:69]
	v_mfma_f32_16x16x32_bf16 v[118:121], v[190:193], v[218:221], v[118:121]
	v_mfma_f32_16x16x32_bf16 v[114:117], v[210:213], v[218:221], v[114:117]
	v_mfma_f32_16x16x32_bf16 v[102:105], v[190:193], v[226:229], v[102:105]
	v_mfma_f32_16x16x32_bf16 v[98:101], v[210:213], v[226:229], v[98:101]
	v_mfma_f32_16x16x32_bf16 v[86:89], v[190:193], v[234:237], v[86:89]
	v_mfma_f32_16x16x32_bf16 v[82:85], v[210:213], v[234:237], v[82:85]
	v_mfma_f32_16x16x32_bf16 v[70:73], v[190:193], v[242:245], v[70:73]
	v_mfma_f32_16x16x32_bf16 v[66:69], v[210:213], v[242:245], v[66:69]
	s_barrier
	s_add_i32 s39, s92, s75
	s_mov_b32 m0, s39
	ds_read_b128 v[214:217], v167 offset:16384
	ds_read_b128 v[218:221], v167 offset:17408
	ds_read_b128 v[222:225], v167 offset:18432
	ds_read_b128 v[226:229], v167 offset:19456
	ds_read_b128 v[230:233], v167 offset:20480
	ds_read_b128 v[234:237], v167 offset:21504
	ds_read_b128 v[238:241], v167 offset:22528
	ds_read_b128 v[242:245], v167 offset:23552
	global_load_lds_dwordx4 v0, s[70:71]
	s_add_i32 m0, s39, 0x2000
	s_add_u32 s50, s70, 0x40000
	s_addc_u32 s51, s71, 0
	s_add_i32 s38, s38, s75
	global_load_lds_dwordx4 v130, s[70:71]
	s_mov_b32 m0, s38
	s_nop 0
	global_load_lds_dwordx4 v0, s[50:51]
	s_add_i32 m0, s38, 0x2000
	s_nop 0
	global_load_lds_dwordx4 v130, s[50:51]
	s_mov_b32 m0, s76
	s_nop 0
	global_load_lds_dwordx4 v134, s[72:73]
	s_mov_b32 m0, s77
	s_nop 0
	global_load_lds_dwordx4 v132, s[72:73]
	s_waitcnt vmcnt(8)
	s_waitcnt lgkmcnt(0)
	s_barrier
	v_mfma_f32_16x16x32_bf16 v[62:65], v[170:173], v[214:217], v[62:65]
	v_mfma_f32_16x16x32_bf16 v[58:61], v[178:181], v[214:217], v[58:61]
	v_mfma_f32_16x16x32_bf16 v[46:49], v[170:173], v[222:225], v[46:49]
	v_mfma_f32_16x16x32_bf16 v[42:45], v[178:181], v[222:225], v[42:45]
	v_mfma_f32_16x16x32_bf16 v[30:33], v[170:173], v[230:233], v[30:33]
	v_mfma_f32_16x16x32_bf16 v[26:29], v[178:181], v[230:233], v[26:29]
	v_mfma_f32_16x16x32_bf16 v[14:17], v[170:173], v[238:241], v[14:17]
	v_mfma_f32_16x16x32_bf16 v[10:13], v[178:181], v[238:241], v[10:13]
	v_mfma_f32_16x16x32_bf16 v[62:65], v[174:177], v[218:221], v[62:65]
	v_mfma_f32_16x16x32_bf16 v[58:61], v[182:185], v[218:221], v[58:61]
	v_mfma_f32_16x16x32_bf16 v[46:49], v[174:177], v[226:229], v[46:49]
	v_mfma_f32_16x16x32_bf16 v[42:45], v[182:185], v[226:229], v[42:45]
	v_mfma_f32_16x16x32_bf16 v[30:33], v[174:177], v[234:237], v[30:33]
	v_mfma_f32_16x16x32_bf16 v[26:29], v[182:185], v[234:237], v[26:29]
	v_mfma_f32_16x16x32_bf16 v[14:17], v[174:177], v[242:245], v[14:17]
	v_mfma_f32_16x16x32_bf16 v[10:13], v[182:185], v[242:245], v[10:13]
	v_mfma_f32_16x16x32_bf16 v[54:57], v[186:189], v[214:217], v[54:57]
	v_mfma_f32_16x16x32_bf16 v[50:53], v[206:209], v[214:217], v[50:53]
	v_mfma_f32_16x16x32_bf16 v[38:41], v[186:189], v[222:225], v[38:41]
	v_mfma_f32_16x16x32_bf16 v[34:37], v[206:209], v[222:225], v[34:37]
	v_mfma_f32_16x16x32_bf16 v[22:25], v[186:189], v[230:233], v[22:25]
	v_mfma_f32_16x16x32_bf16 v[18:21], v[206:209], v[230:233], v[18:21]
	v_mfma_f32_16x16x32_bf16 v[6:9], v[186:189], v[238:241], v[6:9]
	v_mfma_f32_16x16x32_bf16 v[2:5], v[206:209], v[238:241], v[2:5]
	v_mfma_f32_16x16x32_bf16 v[54:57], v[190:193], v[218:221], v[54:57]
	v_mfma_f32_16x16x32_bf16 v[50:53], v[210:213], v[218:221], v[50:53]
	v_mfma_f32_16x16x32_bf16 v[38:41], v[190:193], v[226:229], v[38:41]
	v_mfma_f32_16x16x32_bf16 v[34:37], v[210:213], v[226:229], v[34:37]
	v_mfma_f32_16x16x32_bf16 v[22:25], v[190:193], v[234:237], v[22:25]
	v_mfma_f32_16x16x32_bf16 v[18:21], v[210:213], v[234:237], v[18:21]
	v_mfma_f32_16x16x32_bf16 v[6:9], v[190:193], v[242:245], v[6:9]
	v_mfma_f32_16x16x32_bf16 v[2:5], v[210:213], v[242:245], v[2:5]
	s_barrier
; #define PG8_STAGE(bufoff, gbase, voff) do { _Pragma("unroll") for (int _i = 0; _i < 2; ++_i) \
;         __builtin_amdgcn_global_load_lds((const unsigned*)((const char*)(gbase) + (voff)[_i]), (PG8_LAS unsigned*)(lds + (bufoff) + ldsw + _i * 8192), 16, 0, 0); } while (0)
; #define PG8_LDA(dst, b, h) do { _Pragma("unroll") for (int m = 0; m < 4; ++m) _Pragma("unroll") for (int k = 0; k < 2; ++k) dst[m][k] = *(const PG8_LAS bf16x8*)(lds + PG8_SA(b, h) + aoff + m * 2048 + k * 1024); } while (0)
; #define PG8_LDB(dst, b, h) do { _Pragma("unroll") for (int n = 0; n < 2; ++n) _Pragma("unroll") for (int k = 0; k < 2; ++k) dst[n][k] = *(const PG8_LAS bf16x8*)(lds + PG8_SB(b, h) + boff + n * 2048 + k * 1024); } while (0)
; #define PG8_MMA(ai, bj, At, Bt) do { __builtin_amdgcn_s_setprio(1); _Pragma("unroll") for (int m = 0; m < 4; ++m) _Pragma("unroll") for (int n = 0; n < 2; ++n) _Pragma("unroll") for (int k = 0; k < 2; ++k) \
;         acc[ai][bj][m][n] = __builtin_amdgcn_mfma_f32_16x16x32_bf16(Bt[n][k], At[m][k], acc[ai][bj][m][n], 0, 0, 0); __builtin_amdgcn_s_setprio(0); } while (0)
; #define PG8_WAIT_V(n) asm volatile("s_waitcnt vmcnt(" #n ")" ::: "memory")
; #define PG8_WAIT_L(n) asm volatile("s_waitcnt lgkmcnt(" #n ")" ::: "memory")
; #define PG8_BAR __builtin_amdgcn_s_barrier()
; #define PG8_SCHED __builtin_amdgcn_sched_barrier(0)
; template <class Epi, class Sched, bool ALIGN_EPI = false, bool SP2 = false>
; __device__ __forceinline__ void gemm_phase(PG8_LAS unsigned char* lds, const Gemm g, const Sched& S, const Epi& E, const int tid) {
;     ...
;             PG8_LDB(B0, 1, 0); PG8_LDB(B1, 1, 1); PG8_SCHED; PG8_LDA(At, 1, 0); PG8_STAGE(PG8_SA(0, 1), a2 + hstep, voffA);
;             PG8_WAIT_V(8); PG8_WAIT_L(0); PG8_BAR; PG8_MMA(0, 0, At, B0); PG8_MMA(0, 1, At, B1); PG8_BAR; PG8_SCHED;
;             PG8_LDA(At, 1, 1); PG8_STAGE(PG8_SB(1, 0), b3, voffB); PG8_STAGE(PG8_SB(1, 1), b3 + hstep, voffB); PG8_STAGE(PG8_SA(1, 0), a3, voffA);
;             PG8_WAIT_V(8); PG8_WAIT_L(0); PG8_BAR; PG8_MMA(1, 0, At, B0); PG8_MMA(1, 1, At, B1); PG8_BAR; PG8_SCHED;
	s_add_i32 s38, 0, 0x18000
	s_add_i32 s39, 0, 0x1c000
	ds_read_b128 v[170:173], v150 offset:32768
	ds_read_b128 v[174:177], v150 offset:33792
	ds_read_b128 v[178:181], v150 offset:34816
	ds_read_b128 v[182:185], v150 offset:35840
	ds_read_b128 v[186:189], v150 offset:49152
	ds_read_b128 v[190:193], v150 offset:50176
	ds_read_b128 v[206:209], v150 offset:51200
	ds_read_b128 v[210:213], v150 offset:52224
	s_add_u32 s50, s72, 0x40000
	s_addc_u32 s51, s73, 0
	s_mov_b32 m0, s78
	ds_read_b128 v[214:217], v167 offset:32768
	ds_read_b128 v[218:221], v167 offset:33792
	ds_read_b128 v[222:225], v167 offset:34816
	ds_read_b128 v[226:229], v167 offset:35840
	ds_read_b128 v[230:233], v167 offset:36864
	ds_read_b128 v[234:237], v167 offset:37888
	ds_read_b128 v[238:241], v167 offset:38912
	ds_read_b128 v[242:245], v167 offset:39936
	global_load_lds_dwordx4 v134, s[50:51]
	s_mov_b32 m0, s79
	s_nop 0
	global_load_lds_dwordx4 v132, s[50:51]
	s_waitcnt vmcnt(8)
	s_waitcnt lgkmcnt(0)
	s_barrier
	v_mfma_f32_16x16x32_bf16 v[126:129], v[170:173], v[214:217], v[126:129]
	v_mfma_f32_16x16x32_bf16 v[122:125], v[178:181], v[214:217], v[122:125]
	v_mfma_f32_16x16x32_bf16 v[110:113], v[170:173], v[222:225], v[110:113]
	v_mfma_f32_16x16x32_bf16 v[106:109], v[178:181], v[222:225], v[106:109]
	v_mfma_f32_16x16x32_bf16 v[94:97], v[170:173], v[230:233], v[94:97]
	v_mfma_f32_16x16x32_bf16 v[90:93], v[178:181], v[230:233], v[90:93]
	v_mfma_f32_16x16x32_bf16 v[78:81], v[170:173], v[238:241], v[78:81]
	v_mfma_f32_16x16x32_bf16 v[74:77], v[178:181], v[238:241], v[74:77]
	v_mfma_f32_16x16x32_bf16 v[126:129], v[174:177], v[218:221], v[126:129]
	v_mfma_f32_16x16x32_bf16 v[122:125], v[182:185], v[218:221], v[122:125]
	v_mfma_f32_16x16x32_bf16 v[110:113], v[174:177], v[226:229], v[110:113]
	v_mfma_f32_16x16x32_bf16 v[106:109], v[182:185], v[226:229], v[106:109]
	v_mfma_f32_16x16x32_bf16 v[94:97], v[174:177], v[234:237], v[94:97]
	v_mfma_f32_16x16x32_bf16 v[90:93], v[182:185], v[234:237], v[90:93]
	v_mfma_f32_16x16x32_bf16 v[78:81], v[174:177], v[242:245], v[78:81]
	v_mfma_f32_16x16x32_bf16 v[74:77], v[182:185], v[242:245], v[74:77]
	v_mfma_f32_16x16x32_bf16 v[118:121], v[186:189], v[214:217], v[118:121]
	v_mfma_f32_16x16x32_bf16 v[114:117], v[206:209], v[214:217], v[114:117]
	v_mfma_f32_16x16x32_bf16 v[102:105], v[186:189], v[222:225], v[102:105]
	v_mfma_f32_16x16x32_bf16 v[98:101], v[206:209], v[222:225], v[98:101]
	v_mfma_f32_16x16x32_bf16 v[86:89], v[186:189], v[230:233], v[86:89]
	v_mfma_f32_16x16x32_bf16 v[82:85], v[206:209], v[230:233], v[82:85]
	v_mfma_f32_16x16x32_bf16 v[70:73], v[186:189], v[238:241], v[70:73]
	v_mfma_f32_16x16x32_bf16 v[66:69], v[206:209], v[238:241], v[66:69]
	v_mfma_f32_16x16x32_bf16 v[118:121], v[190:193], v[218:221], v[118:121]
	v_mfma_f32_16x16x32_bf16 v[114:117], v[210:213], v[218:221], v[114:117]
	v_mfma_f32_16x16x32_bf16 v[102:105], v[190:193], v[226:229], v[102:105]
	v_mfma_f32_16x16x32_bf16 v[98:101], v[210:213], v[226:229], v[98:101]
	v_mfma_f32_16x16x32_bf16 v[86:89], v[190:193], v[234:237], v[86:89]
	v_mfma_f32_16x16x32_bf16 v[82:85], v[210:213], v[234:237], v[82:85]
	v_mfma_f32_16x16x32_bf16 v[70:73], v[190:193], v[242:245], v[70:73]
	v_mfma_f32_16x16x32_bf16 v[66:69], v[210:213], v[242:245], v[66:69]
	s_barrier
	s_add_i32 s38, s38, s75
	s_add_u32 s94, s70, 0x80
	s_addc_u32 s95, s71, 0
	s_mov_b32 m0, s38
	ds_read_b128 v[214:217], v167 offset:49152
	ds_read_b128 v[218:221], v167 offset:50176
	ds_read_b128 v[222:225], v167 offset:51200
	ds_read_b128 v[226:229], v167 offset:52224
	ds_read_b128 v[230:233], v167 offset:53248
	ds_read_b128 v[234:237], v167 offset:54272
	ds_read_b128 v[238:241], v167 offset:55296
	ds_read_b128 v[242:245], v167 offset:56320
	global_load_lds_dwordx4 v0, s[94:95]
	s_add_i32 m0, s38, 0x2000
	s_add_u32 s50, s70, 0x40080
	s_addc_u32 s51, s71, 0
	s_add_i32 s38, s39, s75
	global_load_lds_dwordx4 v130, s[94:95]
	s_mov_b32 m0, s38
	s_nop 0
	global_load_lds_dwordx4 v0, s[50:51]
	s_add_i32 m0, s38, 0x2000
	s_nop 0
	global_load_lds_dwordx4 v130, s[50:51]
	s_add_u32 s94, s72, 0x80
	s_addc_u32 s95, s73, 0
	s_mov_b32 m0, s80
	s_nop 0
	global_load_lds_dwordx4 v134, s[94:95]
	s_mov_b32 m0, s81
	s_nop 0
	global_load_lds_dwordx4 v132, s[94:95]
	s_waitcnt vmcnt(8)
	s_waitcnt lgkmcnt(0)
	s_barrier
	v_mfma_f32_16x16x32_bf16 v[62:65], v[170:173], v[214:217], v[62:65]
	v_mfma_f32_16x16x32_bf16 v[58:61], v[178:181], v[214:217], v[58:61]
	v_mfma_f32_16x16x32_bf16 v[46:49], v[170:173], v[222:225], v[46:49]
	v_mfma_f32_16x16x32_bf16 v[42:45], v[178:181], v[222:225], v[42:45]
	v_mfma_f32_16x16x32_bf16 v[30:33], v[170:173], v[230:233], v[30:33]
	v_mfma_f32_16x16x32_bf16 v[26:29], v[178:181], v[230:233], v[26:29]
	v_mfma_f32_16x16x32_bf16 v[14:17], v[170:173], v[238:241], v[14:17]
	v_mfma_f32_16x16x32_bf16 v[10:13], v[178:181], v[238:241], v[10:13]
	v_mfma_f32_16x16x32_bf16 v[62:65], v[174:177], v[218:221], v[62:65]
	v_mfma_f32_16x16x32_bf16 v[58:61], v[182:185], v[218:221], v[58:61]
	v_mfma_f32_16x16x32_bf16 v[46:49], v[174:177], v[226:229], v[46:49]
	v_mfma_f32_16x16x32_bf16 v[42:45], v[182:185], v[226:229], v[42:45]
	v_mfma_f32_16x16x32_bf16 v[30:33], v[174:177], v[234:237], v[30:33]
	v_mfma_f32_16x16x32_bf16 v[26:29], v[182:185], v[234:237], v[26:29]
	v_mfma_f32_16x16x32_bf16 v[14:17], v[174:177], v[242:245], v[14:17]
	v_mfma_f32_16x16x32_bf16 v[10:13], v[182:185], v[242:245], v[10:13]
	v_mfma_f32_16x16x32_bf16 v[54:57], v[186:189], v[214:217], v[54:57]
	v_mfma_f32_16x16x32_bf16 v[50:53], v[206:209], v[214:217], v[50:53]
	v_mfma_f32_16x16x32_bf16 v[38:41], v[186:189], v[222:225], v[38:41]
	v_mfma_f32_16x16x32_bf16 v[34:37], v[206:209], v[222:225], v[34:37]
	v_mfma_f32_16x16x32_bf16 v[22:25], v[186:189], v[230:233], v[22:25]
	v_mfma_f32_16x16x32_bf16 v[18:21], v[206:209], v[230:233], v[18:21]
	v_mfma_f32_16x16x32_bf16 v[6:9], v[186:189], v[238:241], v[6:9]
	v_mfma_f32_16x16x32_bf16 v[2:5], v[206:209], v[238:241], v[2:5]
	v_mfma_f32_16x16x32_bf16 v[54:57], v[190:193], v[218:221], v[54:57]
	v_mfma_f32_16x16x32_bf16 v[50:53], v[210:213], v[218:221], v[50:53]
	v_mfma_f32_16x16x32_bf16 v[38:41], v[190:193], v[226:229], v[38:41]
	v_mfma_f32_16x16x32_bf16 v[34:37], v[210:213], v[226:229], v[34:37]
	v_mfma_f32_16x16x32_bf16 v[22:25], v[190:193], v[234:237], v[22:25]
	v_mfma_f32_16x16x32_bf16 v[18:21], v[210:213], v[234:237], v[18:21]
	v_mfma_f32_16x16x32_bf16 v[6:9], v[190:193], v[242:245], v[6:9]
	v_mfma_f32_16x16x32_bf16 v[2:5], v[210:213], v[242:245], v[2:5]
	s_barrier
	s_add_i32 s91, s91, 2
	s_add_u32 s68, s68, 0x100
	s_addc_u32 s69, s69, 0
	s_cmp_gt_u32 s91, 13
	s_cbranch_scc1 .LBB0_90

;     __device__ __forceinline__ void stage_rs(const Unit& u, int tid, int wid) const { stage_rs_lds(SS, rsl, u, tid, wid); }
;     __device__ __forceinline__ void stage_rs(const Unit& u, int tid, int wid) const { stage_rs_lds(SS, rsl, u, tid, wid); }
; #define PG8_STAGE(bufoff, gbase, voff) do { _Pragma("unroll") for (int _i = 0; _i < 2; ++_i) \
;         __builtin_amdgcn_global_load_lds((const unsigned*)((const char*)(gbase) + (voff)[_i]), (PG8_LAS unsigned*)(lds + (bufoff) + ldsw + _i * 8192), 16, 0, 0); } while (0)
; #define PG8_LDA(dst, b, h) do { _Pragma("unroll") for (int m = 0; m < 4; ++m) _Pragma("unroll") for (int k = 0; k < 2; ++k) dst[m][k] = *(const PG8_LAS bf16x8*)(lds + PG8_SA(b, h) + aoff + m * 2048 + k * 1024); } while (0)
; #define PG8_LDB(dst, b, h) do { _Pragma("unroll") for (int n = 0; n < 2; ++n) _Pragma("unroll") for (int k = 0; k < 2; ++k) dst[n][k] = *(const PG8_LAS bf16x8*)(lds + PG8_SB(b, h) + boff + n * 2048 + k * 1024); } while (0)
; #define PG8_WAIT_V(n) asm volatile("s_waitcnt vmcnt(" #n ")" ::: "memory")
; template <class Epi, class Sched, bool ALIGN_EPI = false, bool SP2 = false>
; __device__ __forceinline__ void gemm_phase(PG8_LAS unsigned char* lds, const Gemm g, const Sched& S, const Epi& E, const int tid) {
;     ...
;             const bool last = (t == nt - 2);
;             if constexpr (Epi::RS_LDS) { if (t == nt - 4) E.stage_rs(cur, tid, wid); }
;             if constexpr (Epi::PREFETCH) { if (t >= nt - 8) E.prefetch(cur, lds, tid, wid, (t - (nt - 8)) >> 1); }
;             const char* a1 = cA + (size_t)(t + 1) * kstep;
;             const char* a2 = last ? nA : cA + (size_t)(t + 2) * kstep; const char* b2 = last ? nB : cB + (size_t)(t + 2) * kstep;
;             const char* a3 = a2 + kstep; const char* b3 = b2 + kstep;
;             if (last && has_next) S.a_ready(nxt);
;             if constexpr (SP2) {
;             PG8_LDB(B0, 0, 0); PG8_LDB(B1, 0, 1); PG8_SCHED; PG8_LDA(At, 0, 0); PG8_STAGE(PG8_SA(1, 1), a1 + hstep, voffA);
;             PG8_WAIT_V(8); PG8_WAIT_L(0); PG8_BAR; PG8_MMA(0, 0, At, B0); PG8_MMA(0, 1, At, B1); PG8_BAR; PG8_SCHED;
;             PG8_LDA(At, 0, 1); PG8_STAGE(PG8_SB(0, 0), b2, voffB); PG8_STAGE(PG8_SB(0, 1), b2 + hstep, voffB); PG8_STAGE(PG8_SA(0, 0), a2, voffA);
;             PG8_WAIT_V(8); PG8_WAIT_L(0); PG8_BAR; PG8_MMA(1, 0, At, B0); PG8_MMA(1, 1, At, B1); PG8_BAR; PG8_SCHED;
.LBB0_208:
	s_add_u32 s38, s10, s12
	s_addc_u32 s39, s11, s13
	s_add_u32 s38, s38, 0x100
	s_addc_u32 s39, s39, 0
	s_add_u32 s51, vcc_lo, s12
	s_addc_u32 s74, vcc_hi, s13
	s_add_i32 s59, 0, 0x10000
	s_cmpk_eq_i32 s12, 0x700
	s_cselect_b32 s77, s49, s39
	s_cselect_b32 s76, s78, s38
	s_cselect_b32 s75, s69, s74
	s_cselect_b32 s74, s79, s51
	s_add_i32 s51, 0, 0x14000
	ds_read_b128 v[170:173], v0
	ds_read_b128 v[174:177], v0 offset:1024
	ds_read_b128 v[178:181], v0 offset:2048
	ds_read_b128 v[182:185], v0 offset:3072
	ds_read_b128 v[186:189], v0 offset:16384
	ds_read_b128 v[190:193], v0 offset:17408
	ds_read_b128 v[206:209], v0 offset:18432
	ds_read_b128 v[210:213], v0 offset:19456
	s_add_i32 m0, s84, 0xc000
	ds_read_b128 v[214:217], v167
	ds_read_b128 v[218:221], v167 offset:1024
	ds_read_b128 v[222:225], v167 offset:2048
	ds_read_b128 v[226:229], v167 offset:3072
	ds_read_b128 v[230:233], v167 offset:4096
	ds_read_b128 v[234:237], v167 offset:5120
	ds_read_b128 v[238:241], v167 offset:6144
	ds_read_b128 v[242:245], v167 offset:7168
	global_load_lds_dwordx4 v148, s[38:39]
	s_add_i32 m0, s84, 0xe000
	s_nop 0
	global_load_lds_dwordx4 v150, s[38:39]
	s_waitcnt vmcnt(8)
	s_waitcnt lgkmcnt(0)
	s_barrier
	v_mfma_f32_16x16x32_bf16 v[126:129], v[170:173], v[214:217], v[126:129]
	v_mfma_f32_16x16x32_bf16 v[122:125], v[178:181], v[214:217], v[122:125]
	v_mfma_f32_16x16x32_bf16 v[110:113], v[170:173], v[222:225], v[110:113]
	v_mfma_f32_16x16x32_bf16 v[106:109], v[178:181], v[222:225], v[106:109]
	v_mfma_f32_16x16x32_bf16 v[94:97], v[170:173], v[230:233], v[94:97]
	v_mfma_f32_16x16x32_bf16 v[90:93], v[178:181], v[230:233], v[90:93]
	v_mfma_f32_16x16x32_bf16 v[78:81], v[170:173], v[238:241], v[78:81]
	v_mfma_f32_16x16x32_bf16 v[74:77], v[178:181], v[238:241], v[74:77]
	v_mfma_f32_16x16x32_bf16 v[126:129], v[174:177], v[218:221], v[126:129]
	v_mfma_f32_16x16x32_bf16 v[122:125], v[182:185], v[218:221], v[122:125]
	v_mfma_f32_16x16x32_bf16 v[110:113], v[174:177], v[226:229], v[110:113]
	v_mfma_f32_16x16x32_bf16 v[106:109], v[182:185], v[226:229], v[106:109]
	v_mfma_f32_16x16x32_bf16 v[94:97], v[174:177], v[234:237], v[94:97]
	v_mfma_f32_16x16x32_bf16 v[90:93], v[182:185], v[234:237], v[90:93]
	v_mfma_f32_16x16x32_bf16 v[78:81], v[174:177], v[242:245], v[78:81]
	v_mfma_f32_16x16x32_bf16 v[74:77], v[182:185], v[242:245], v[74:77]
	v_mfma_f32_16x16x32_bf16 v[118:121], v[186:189], v[214:217], v[118:121]
	v_mfma_f32_16x16x32_bf16 v[114:117], v[206:209], v[214:217], v[114:117]
	v_mfma_f32_16x16x32_bf16 v[102:105], v[186:189], v[222:225], v[102:105]
	v_mfma_f32_16x16x32_bf16 v[98:101], v[206:209], v[222:225], v[98:101]
	v_mfma_f32_16x16x32_bf16 v[86:89], v[186:189], v[230:233], v[86:89]
	v_mfma_f32_16x16x32_bf16 v[82:85], v[206:209], v[230:233], v[82:85]
	v_mfma_f32_16x16x32_bf16 v[70:73], v[186:189], v[238:241], v[70:73]
	v_mfma_f32_16x16x32_bf16 v[66:69], v[206:209], v[238:241], v[66:69]
	v_mfma_f32_16x16x32_bf16 v[118:121], v[190:193], v[218:221], v[118:121]
	v_mfma_f32_16x16x32_bf16 v[114:117], v[210:213], v[218:221], v[114:117]
	v_mfma_f32_16x16x32_bf16 v[102:105], v[190:193], v[226:229], v[102:105]
	v_mfma_f32_16x16x32_bf16 v[98:101], v[210:213], v[226:229], v[98:101]
	v_mfma_f32_16x16x32_bf16 v[86:89], v[190:193], v[234:237], v[86:89]
	v_mfma_f32_16x16x32_bf16 v[82:85], v[210:213], v[234:237], v[82:85]
	v_mfma_f32_16x16x32_bf16 v[70:73], v[190:193], v[242:245], v[70:73]
	v_mfma_f32_16x16x32_bf16 v[66:69], v[210:213], v[242:245], v[66:69]
	s_barrier
	s_add_i32 s38, s59, s83
	s_mov_b32 m0, s38
	ds_read_b128 v[214:217], v167 offset:16384
	ds_read_b128 v[218:221], v167 offset:17408
	ds_read_b128 v[222:225], v167 offset:18432
	ds_read_b128 v[226:229], v167 offset:19456
	ds_read_b128 v[230:233], v167 offset:20480
	ds_read_b128 v[234:237], v167 offset:21504
	ds_read_b128 v[238:241], v167 offset:22528
	ds_read_b128 v[242:245], v167 offset:23552
	global_load_lds_dwordx4 v134, s[74:75]
	s_add_i32 m0, s38, 0x2000
	s_add_u32 s38, s74, 0x40000
	s_addc_u32 s39, s75, 0
	s_add_i32 s51, s51, s83
	global_load_lds_dwordx4 v130, s[74:75]
	s_mov_b32 m0, s51
	s_nop 0
	global_load_lds_dwordx4 v134, s[38:39]
	s_add_i32 m0, s51, 0x2000
	s_nop 0
	global_load_lds_dwordx4 v130, s[38:39]
	s_mov_b32 m0, s84
	s_nop 0
	global_load_lds_dwordx4 v136, s[76:77]
	s_mov_b32 m0, s85
	s_nop 0
	global_load_lds_dwordx4 v132, s[76:77]
	s_waitcnt vmcnt(8)
	s_waitcnt lgkmcnt(0)
	s_barrier
	v_mfma_f32_16x16x32_bf16 v[62:65], v[170:173], v[214:217], v[62:65]
	v_mfma_f32_16x16x32_bf16 v[58:61], v[178:181], v[214:217], v[58:61]
	v_mfma_f32_16x16x32_bf16 v[46:49], v[170:173], v[222:225], v[46:49]
	v_mfma_f32_16x16x32_bf16 v[42:45], v[178:181], v[222:225], v[42:45]
	v_mfma_f32_16x16x32_bf16 v[30:33], v[170:173], v[230:233], v[30:33]
	v_mfma_f32_16x16x32_bf16 v[26:29], v[178:181], v[230:233], v[26:29]
	v_mfma_f32_16x16x32_bf16 v[14:17], v[170:173], v[238:241], v[14:17]
	v_mfma_f32_16x16x32_bf16 v[10:13], v[178:181], v[238:241], v[10:13]
	v_mfma_f32_16x16x32_bf16 v[62:65], v[174:177], v[218:221], v[62:65]
	v_mfma_f32_16x16x32_bf16 v[58:61], v[182:185], v[218:221], v[58:61]
	v_mfma_f32_16x16x32_bf16 v[46:49], v[174:177], v[226:229], v[46:49]
	v_mfma_f32_16x16x32_bf16 v[42:45], v[182:185], v[226:229], v[42:45]
	v_mfma_f32_16x16x32_bf16 v[30:33], v[174:177], v[234:237], v[30:33]
	v_mfma_f32_16x16x32_bf16 v[26:29], v[182:185], v[234:237], v[26:29]
	v_mfma_f32_16x16x32_bf16 v[14:17], v[174:177], v[242:245], v[14:17]
	v_mfma_f32_16x16x32_bf16 v[10:13], v[182:185], v[242:245], v[10:13]
	v_mfma_f32_16x16x32_bf16 v[54:57], v[186:189], v[214:217], v[54:57]
	v_mfma_f32_16x16x32_bf16 v[50:53], v[206:209], v[214:217], v[50:53]
	v_mfma_f32_16x16x32_bf16 v[38:41], v[186:189], v[222:225], v[38:41]
	v_mfma_f32_16x16x32_bf16 v[34:37], v[206:209], v[222:225], v[34:37]
	v_mfma_f32_16x16x32_bf16 v[22:25], v[186:189], v[230:233], v[22:25]
	v_mfma_f32_16x16x32_bf16 v[18:21], v[206:209], v[230:233], v[18:21]
	v_mfma_f32_16x16x32_bf16 v[6:9], v[186:189], v[238:241], v[6:9]
	v_mfma_f32_16x16x32_bf16 v[2:5], v[206:209], v[238:241], v[2:5]
	v_mfma_f32_16x16x32_bf16 v[54:57], v[190:193], v[218:221], v[54:57]
	v_mfma_f32_16x16x32_bf16 v[50:53], v[210:213], v[218:221], v[50:53]
	v_mfma_f32_16x16x32_bf16 v[38:41], v[190:193], v[226:229], v[38:41]
	v_mfma_f32_16x16x32_bf16 v[34:37], v[210:213], v[226:229], v[34:37]
	v_mfma_f32_16x16x32_bf16 v[22:25], v[190:193], v[234:237], v[22:25]
	v_mfma_f32_16x16x32_bf16 v[18:21], v[210:213], v[234:237], v[18:21]
	v_mfma_f32_16x16x32_bf16 v[6:9], v[190:193], v[242:245], v[6:9]
	v_mfma_f32_16x16x32_bf16 v[2:5], v[210:213], v[242:245], v[2:5]
	s_barrier
; #define PG8_STAGE(bufoff, gbase, voff) do { _Pragma("unroll") for (int _i = 0; _i < 2; ++_i) \
;         __builtin_amdgcn_global_load_lds((const unsigned*)((const char*)(gbase) + (voff)[_i]), (PG8_LAS unsigned*)(lds + (bufoff) + ldsw + _i * 8192), 16, 0, 0); } while (0)
; #define PG8_LDA(dst, b, h) do { _Pragma("unroll") for (int m = 0; m < 4; ++m) _Pragma("unroll") for (int k = 0; k < 2; ++k) dst[m][k] = *(const PG8_LAS bf16x8*)(lds + PG8_SA(b, h) + aoff + m * 2048 + k * 1024); } while (0)
; #define PG8_LDB(dst, b, h) do { _Pragma("unroll") for (int n = 0; n < 2; ++n) _Pragma("unroll") for (int k = 0; k < 2; ++k) dst[n][k] = *(const PG8_LAS bf16x8*)(lds + PG8_SB(b, h) + boff + n * 2048 + k * 1024); } while (0)
; #define PG8_MMA(ai, bj, At, Bt) do { __builtin_amdgcn_s_setprio(1); _Pragma("unroll") for (int m = 0; m < 4; ++m) _Pragma("unroll") for (int n = 0; n < 2; ++n) _Pragma("unroll") for (int k = 0; k < 2; ++k) \
;         acc[ai][bj][m][n] = __builtin_amdgcn_mfma_f32_16x16x32_bf16(Bt[n][k], At[m][k], acc[ai][bj][m][n], 0, 0, 0); __builtin_amdgcn_s_setprio(0); } while (0)
; #define PG8_WAIT_V(n) asm volatile("s_waitcnt vmcnt(" #n ")" ::: "memory")
; #define PG8_WAIT_L(n) asm volatile("s_waitcnt lgkmcnt(" #n ")" ::: "memory")
; #define PG8_BAR __builtin_amdgcn_s_barrier()
; #define PG8_SCHED __builtin_amdgcn_sched_barrier(0)
; template <class Epi, class Sched, bool ALIGN_EPI = false, bool SP2 = false>
; __device__ __forceinline__ void gemm_phase(PG8_LAS unsigned char* lds, const Gemm g, const Sched& S, const Epi& E, const int tid) {
;     ...
;             PG8_LDB(B0, 1, 0); PG8_LDB(B1, 1, 1); PG8_SCHED; PG8_LDA(At, 1, 0); PG8_STAGE(PG8_SA(0, 1), a2 + hstep, voffA);
;             PG8_WAIT_V(8); PG8_WAIT_L(0); PG8_BAR; PG8_MMA(0, 0, At, B0); PG8_MMA(0, 1, At, B1); PG8_BAR; PG8_SCHED;
;             PG8_LDA(At, 1, 1); PG8_STAGE(PG8_SB(1, 0), b3, voffB); PG8_STAGE(PG8_SB(1, 1), b3 + hstep, voffB); PG8_STAGE(PG8_SA(1, 0), a3, voffA);
;             PG8_WAIT_V(8); PG8_WAIT_L(0); PG8_BAR; PG8_MMA(1, 0, At, B0); PG8_MMA(1, 1, At, B1); PG8_BAR; PG8_SCHED;
	s_add_i32 s51, 0, 0x18000
	s_add_i32 s59, 0, 0x1c000
	ds_read_b128 v[170:173], v0 offset:32768
	ds_read_b128 v[174:177], v0 offset:33792
	ds_read_b128 v[178:181], v0 offset:34816
	ds_read_b128 v[182:185], v0 offset:35840
	ds_read_b128 v[186:189], v0 offset:49152
	ds_read_b128 v[190:193], v0 offset:50176
	ds_read_b128 v[206:209], v0 offset:51200
	ds_read_b128 v[210:213], v0 offset:52224
	s_add_u32 s38, s76, 0x40000
	s_addc_u32 s39, s77, 0
	s_mov_b32 m0, s86
	ds_read_b128 v[214:217], v167 offset:32768
	ds_read_b128 v[218:221], v167 offset:33792
	ds_read_b128 v[222:225], v167 offset:34816
	ds_read_b128 v[226:229], v167 offset:35840
	ds_read_b128 v[230:233], v167 offset:36864
	ds_read_b128 v[234:237], v167 offset:37888
	ds_read_b128 v[238:241], v167 offset:38912
	ds_read_b128 v[242:245], v167 offset:39936
	global_load_lds_dwordx4 v136, s[38:39]
	s_mov_b32 m0, s87
	s_nop 0
	global_load_lds_dwordx4 v132, s[38:39]
	s_waitcnt vmcnt(8)
	s_waitcnt lgkmcnt(0)
	s_barrier
	v_mfma_f32_16x16x32_bf16 v[126:129], v[170:173], v[214:217], v[126:129]
	v_mfma_f32_16x16x32_bf16 v[122:125], v[178:181], v[214:217], v[122:125]
	v_mfma_f32_16x16x32_bf16 v[110:113], v[170:173], v[222:225], v[110:113]
	v_mfma_f32_16x16x32_bf16 v[106:109], v[178:181], v[222:225], v[106:109]
	v_mfma_f32_16x16x32_bf16 v[94:97], v[170:173], v[230:233], v[94:97]
	v_mfma_f32_16x16x32_bf16 v[90:93], v[178:181], v[230:233], v[90:93]
	v_mfma_f32_16x16x32_bf16 v[78:81], v[170:173], v[238:241], v[78:81]
	v_mfma_f32_16x16x32_bf16 v[74:77], v[178:181], v[238:241], v[74:77]
	v_mfma_f32_16x16x32_bf16 v[126:129], v[174:177], v[218:221], v[126:129]
	v_mfma_f32_16x16x32_bf16 v[122:125], v[182:185], v[218:221], v[122:125]
	v_mfma_f32_16x16x32_bf16 v[110:113], v[174:177], v[226:229], v[110:113]
	v_mfma_f32_16x16x32_bf16 v[106:109], v[182:185], v[226:229], v[106:109]
	v_mfma_f32_16x16x32_bf16 v[94:97], v[174:177], v[234:237], v[94:97]
	v_mfma_f32_16x16x32_bf16 v[90:93], v[182:185], v[234:237], v[90:93]
	v_mfma_f32_16x16x32_bf16 v[78:81], v[174:177], v[242:245], v[78:81]
	v_mfma_f32_16x16x32_bf16 v[74:77], v[182:185], v[242:245], v[74:77]
	v_mfma_f32_16x16x32_bf16 v[118:121], v[186:189], v[214:217], v[118:121]
	v_mfma_f32_16x16x32_bf16 v[114:117], v[206:209], v[214:217], v[114:117]
	v_mfma_f32_16x16x32_bf16 v[102:105], v[186:189], v[222:225], v[102:105]
	v_mfma_f32_16x16x32_bf16 v[98:101], v[206:209], v[222:225], v[98:101]
	v_mfma_f32_16x16x32_bf16 v[86:89], v[186:189], v[230:233], v[86:89]
	v_mfma_f32_16x16x32_bf16 v[82:85], v[206:209], v[230:233], v[82:85]
	v_mfma_f32_16x16x32_bf16 v[70:73], v[186:189], v[238:241], v[70:73]
	v_mfma_f32_16x16x32_bf16 v[66:69], v[206:209], v[238:241], v[66:69]
	v_mfma_f32_16x16x32_bf16 v[118:121], v[190:193], v[218:221], v[118:121]
	v_mfma_f32_16x16x32_bf16 v[114:117], v[210:213], v[218:221], v[114:117]
	v_mfma_f32_16x16x32_bf16 v[102:105], v[190:193], v[226:229], v[102:105]
	v_mfma_f32_16x16x32_bf16 v[98:101], v[210:213], v[226:229], v[98:101]
	v_mfma_f32_16x16x32_bf16 v[86:89], v[190:193], v[234:237], v[86:89]
	v_mfma_f32_16x16x32_bf16 v[82:85], v[210:213], v[234:237], v[82:85]
	v_mfma_f32_16x16x32_bf16 v[70:73], v[190:193], v[242:245], v[70:73]
	v_mfma_f32_16x16x32_bf16 v[66:69], v[210:213], v[242:245], v[66:69]
	s_barrier
	s_add_i32 s38, s51, s83
	s_add_i32 m0, s38, 0xffffff80
	ds_read_b128 v[214:217], v167 offset:49152
	ds_read_b128 v[218:221], v167 offset:50176
	ds_read_b128 v[222:225], v167 offset:51200
	ds_read_b128 v[226:229], v167 offset:52224
	ds_read_b128 v[230:233], v167 offset:53248
	ds_read_b128 v[234:237], v167 offset:54272
	ds_read_b128 v[238:241], v167 offset:55296
	ds_read_b128 v[242:245], v167 offset:56320
	global_load_lds_dwordx4 v134, s[74:75] offset:128
	s_add_i32 m0, s38, 0x1f80
	s_add_u32 s38, s74, 0x40080
	s_addc_u32 s39, s75, 0
	s_add_i32 s51, s59, s83
	global_load_lds_dwordx4 v130, s[74:75] offset:128
	s_mov_b32 m0, s51
	s_nop 0
	global_load_lds_dwordx4 v134, s[38:39]
	s_add_i32 m0, s51, 0x2000
	s_nop 0
	global_load_lds_dwordx4 v130, s[38:39]
	s_add_i32 m0, s88, 0xffffff80
	s_nop 0
	global_load_lds_dwordx4 v136, s[76:77] offset:128
	s_add_i32 m0, s89, 0xffffff80
	s_nop 0
	global_load_lds_dwordx4 v132, s[76:77] offset:128
	s_waitcnt vmcnt(8)
	s_waitcnt lgkmcnt(0)
	s_barrier
	v_mfma_f32_16x16x32_bf16 v[62:65], v[170:173], v[214:217], v[62:65]
	v_mfma_f32_16x16x32_bf16 v[58:61], v[178:181], v[214:217], v[58:61]
	v_mfma_f32_16x16x32_bf16 v[46:49], v[170:173], v[222:225], v[46:49]
	v_mfma_f32_16x16x32_bf16 v[42:45], v[178:181], v[222:225], v[42:45]
	v_mfma_f32_16x16x32_bf16 v[30:33], v[170:173], v[230:233], v[30:33]
	v_mfma_f32_16x16x32_bf16 v[26:29], v[178:181], v[230:233], v[26:29]
	v_mfma_f32_16x16x32_bf16 v[14:17], v[170:173], v[238:241], v[14:17]
	v_mfma_f32_16x16x32_bf16 v[10:13], v[178:181], v[238:241], v[10:13]
	v_mfma_f32_16x16x32_bf16 v[62:65], v[174:177], v[218:221], v[62:65]
	v_mfma_f32_16x16x32_bf16 v[58:61], v[182:185], v[218:221], v[58:61]
	v_mfma_f32_16x16x32_bf16 v[46:49], v[174:177], v[226:229], v[46:49]
	v_mfma_f32_16x16x32_bf16 v[42:45], v[182:185], v[226:229], v[42:45]
	v_mfma_f32_16x16x32_bf16 v[30:33], v[174:177], v[234:237], v[30:33]
	v_mfma_f32_16x16x32_bf16 v[26:29], v[182:185], v[234:237], v[26:29]
	v_mfma_f32_16x16x32_bf16 v[14:17], v[174:177], v[242:245], v[14:17]
	v_mfma_f32_16x16x32_bf16 v[10:13], v[182:185], v[242:245], v[10:13]
	v_mfma_f32_16x16x32_bf16 v[54:57], v[186:189], v[214:217], v[54:57]
	v_mfma_f32_16x16x32_bf16 v[50:53], v[206:209], v[214:217], v[50:53]
	v_mfma_f32_16x16x32_bf16 v[38:41], v[186:189], v[222:225], v[38:41]
	v_mfma_f32_16x16x32_bf16 v[34:37], v[206:209], v[222:225], v[34:37]
	v_mfma_f32_16x16x32_bf16 v[22:25], v[186:189], v[230:233], v[22:25]
	v_mfma_f32_16x16x32_bf16 v[18:21], v[206:209], v[230:233], v[18:21]
	v_mfma_f32_16x16x32_bf16 v[6:9], v[186:189], v[238:241], v[6:9]
	v_mfma_f32_16x16x32_bf16 v[2:5], v[206:209], v[238:241], v[2:5]
	v_mfma_f32_16x16x32_bf16 v[54:57], v[190:193], v[218:221], v[54:57]
	v_mfma_f32_16x16x32_bf16 v[50:53], v[210:213], v[218:221], v[50:53]
	v_mfma_f32_16x16x32_bf16 v[38:41], v[190:193], v[226:229], v[38:41]
	v_mfma_f32_16x16x32_bf16 v[34:37], v[210:213], v[226:229], v[34:37]
	v_mfma_f32_16x16x32_bf16 v[22:25], v[190:193], v[234:237], v[22:25]
	v_mfma_f32_16x16x32_bf16 v[18:21], v[210:213], v[234:237], v[18:21]
	v_mfma_f32_16x16x32_bf16 v[6:9], v[190:193], v[242:245], v[6:9]
	v_mfma_f32_16x16x32_bf16 v[2:5], v[210:213], v[242:245], v[2:5]
	s_barrier
	s_add_i32 s50, s50, 2
	s_add_u32 s12, s12, 0x100
	s_addc_u32 s13, s13, 0
	s_cmp_gt_u32 s50, 13
	s_cbranch_scc1 .LBB0_211

;     __device__ __forceinline__ void stage_rs(const Unit& u, int tid, int wid) const { stage_rs_lds(SS, rsl, u, tid, wid); }
;     __device__ __forceinline__ void stage_rs(const Unit& u, int tid, int wid) const { stage_rs_lds(SS, rsl, u, tid, wid); }
; #define PG8_STAGE(bufoff, gbase, voff) do { _Pragma("unroll") for (int _i = 0; _i < 2; ++_i) \
;         __builtin_amdgcn_global_load_lds((const unsigned*)((const char*)(gbase) + (voff)[_i]), (PG8_LAS unsigned*)(lds + (bufoff) + ldsw + _i * 8192), 16, 0, 0); } while (0)
; #define PG8_LDA(dst, b, h) do { _Pragma("unroll") for (int m = 0; m < 4; ++m) _Pragma("unroll") for (int k = 0; k < 2; ++k) dst[m][k] = *(const PG8_LAS bf16x8*)(lds + PG8_SA(b, h) + aoff + m * 2048 + k * 1024); } while (0)
; #define PG8_LDB(dst, b, h) do { _Pragma("unroll") for (int n = 0; n < 2; ++n) _Pragma("unroll") for (int k = 0; k < 2; ++k) dst[n][k] = *(const PG8_LAS bf16x8*)(lds + PG8_SB(b, h) + boff + n * 2048 + k * 1024); } while (0)
; #define PG8_WAIT_V(n) asm volatile("s_waitcnt vmcnt(" #n ")" ::: "memory")
; template <class Epi, class Sched, bool ALIGN_EPI = false, bool SP2 = false>
; __device__ __forceinline__ void gemm_phase(PG8_LAS unsigned char* lds, const Gemm g, const Sched& S, const Epi& E, const int tid) {
;     ...
;             const bool last = (t == nt - 2);
;             if constexpr (Epi::RS_LDS) { if (t == nt - 4) E.stage_rs(cur, tid, wid); }
;             if constexpr (Epi::PREFETCH) { if (t >= nt - 8) E.prefetch(cur, lds, tid, wid, (t - (nt - 8)) >> 1); }
;             const char* a1 = cA + (size_t)(t + 1) * kstep;
;             const char* a2 = last ? nA : cA + (size_t)(t + 2) * kstep; const char* b2 = last ? nB : cB + (size_t)(t + 2) * kstep;
;             const char* a3 = a2 + kstep; const char* b3 = b2 + kstep;
;             if (last && has_next) S.a_ready(nxt);
;             if constexpr (SP2) {
;             PG8_LDB(B0, 0, 0); PG8_LDB(B1, 0, 1); PG8_SCHED; PG8_LDA(At, 0, 0); PG8_STAGE(PG8_SA(1, 1), a1 + hstep, voffA);
;             PG8_WAIT_V(8); PG8_WAIT_L(0); PG8_BAR; PG8_MMA(0, 0, At, B0); PG8_MMA(0, 1, At, B1); PG8_BAR; PG8_SCHED;
;             PG8_LDA(At, 0, 1); PG8_STAGE(PG8_SB(0, 0), b2, voffB); PG8_STAGE(PG8_SB(0, 1), b2 + hstep, voffB); PG8_STAGE(PG8_SA(0, 0), a2, voffA);
;             PG8_WAIT_V(8); PG8_WAIT_L(0); PG8_BAR; PG8_MMA(1, 0, At, B0); PG8_MMA(1, 1, At, B1); PG8_BAR; PG8_SCHED;
.LBB0_618:
	s_add_i32 s85, s70, 2
	s_add_u32 s38, s68, 0x80
	s_addc_u32 s39, s69, 0
	s_add_i32 s59, 0, 0x10000
	s_cmp_eq_u32 s81, s70
	s_cselect_b32 s71, s11, s39
	s_cselect_b32 s70, s10, s38
	s_cselect_b32 s39, s67, s51
	s_cselect_b32 s38, s66, s50
	s_add_i32 s86, 0, 0x14000
	v_add_u32_e32 v142, s59, v205
	v_add_u32_e32 v180, s86, v205
	ds_read_b128 v[130:133], v142
	ds_read_b128 v[134:137], v142 offset:1024
	ds_read_b128 v[138:141], v142 offset:2048
	ds_read_b128 v[142:145], v142 offset:3072
	ds_read_b128 v[146:149], v180
	ds_read_b128 v[150:153], v180 offset:1024
	ds_read_b128 v[176:179], v180 offset:2048
	ds_read_b128 v[180:183], v180 offset:3072
	s_add_i32 m0, s73, 0xc000
	ds_read_b128 v[184:187], v207
	ds_read_b128 v[188:191], v207 offset:1024
	ds_read_b128 v[208:211], v207 offset:2048
	ds_read_b128 v[212:215], v207 offset:3072
	ds_read_b128 v[216:219], v207 offset:4096
	ds_read_b128 v[220:223], v207 offset:5120
	ds_read_b128 v[224:227], v207 offset:6144
	ds_read_b128 v[228:231], v207 offset:7168
	global_load_lds_dwordx4 v172, s[68:69]
	s_add_i32 m0, s73, 0xe000
	s_nop 0
	global_load_lds_dwordx4 v174, s[68:69]
	s_waitcnt vmcnt(8)
	s_waitcnt lgkmcnt(0)
	s_barrier
	v_mfma_f32_16x16x32_bf16 v[126:129], v[130:133], v[184:187], v[126:129]
	v_mfma_f32_16x16x32_bf16 v[122:125], v[138:141], v[184:187], v[122:125]
	v_mfma_f32_16x16x32_bf16 v[110:113], v[130:133], v[208:211], v[110:113]
	v_mfma_f32_16x16x32_bf16 v[106:109], v[138:141], v[208:211], v[106:109]
	v_mfma_f32_16x16x32_bf16 v[94:97], v[130:133], v[216:219], v[94:97]
	v_mfma_f32_16x16x32_bf16 v[90:93], v[138:141], v[216:219], v[90:93]
	v_mfma_f32_16x16x32_bf16 v[78:81], v[130:133], v[224:227], v[78:81]
	v_mfma_f32_16x16x32_bf16 v[74:77], v[138:141], v[224:227], v[74:77]
	v_mfma_f32_16x16x32_bf16 v[126:129], v[134:137], v[188:191], v[126:129]
	v_mfma_f32_16x16x32_bf16 v[122:125], v[142:145], v[188:191], v[122:125]
	v_mfma_f32_16x16x32_bf16 v[110:113], v[134:137], v[212:215], v[110:113]
	v_mfma_f32_16x16x32_bf16 v[106:109], v[142:145], v[212:215], v[106:109]
	v_mfma_f32_16x16x32_bf16 v[94:97], v[134:137], v[220:223], v[94:97]
	v_mfma_f32_16x16x32_bf16 v[90:93], v[142:145], v[220:223], v[90:93]
	v_mfma_f32_16x16x32_bf16 v[78:81], v[134:137], v[228:231], v[78:81]
	v_mfma_f32_16x16x32_bf16 v[74:77], v[142:145], v[228:231], v[74:77]
	v_mfma_f32_16x16x32_bf16 v[118:121], v[146:149], v[184:187], v[118:121]
	v_mfma_f32_16x16x32_bf16 v[114:117], v[176:179], v[184:187], v[114:117]
	v_mfma_f32_16x16x32_bf16 v[102:105], v[146:149], v[208:211], v[102:105]
	v_mfma_f32_16x16x32_bf16 v[98:101], v[176:179], v[208:211], v[98:101]
	v_mfma_f32_16x16x32_bf16 v[86:89], v[146:149], v[216:219], v[86:89]
	v_mfma_f32_16x16x32_bf16 v[82:85], v[176:179], v[216:219], v[82:85]
	v_mfma_f32_16x16x32_bf16 v[70:73], v[146:149], v[224:227], v[70:73]
	v_mfma_f32_16x16x32_bf16 v[66:69], v[176:179], v[224:227], v[66:69]
	v_mfma_f32_16x16x32_bf16 v[118:121], v[150:153], v[188:191], v[118:121]
	v_mfma_f32_16x16x32_bf16 v[114:117], v[180:183], v[188:191], v[114:117]
	v_mfma_f32_16x16x32_bf16 v[102:105], v[150:153], v[212:215], v[102:105]
	v_mfma_f32_16x16x32_bf16 v[98:101], v[180:183], v[212:215], v[98:101]
	v_mfma_f32_16x16x32_bf16 v[86:89], v[150:153], v[220:223], v[86:89]
	v_mfma_f32_16x16x32_bf16 v[82:85], v[180:183], v[220:223], v[82:85]
	v_mfma_f32_16x16x32_bf16 v[70:73], v[150:153], v[228:231], v[70:73]
	v_mfma_f32_16x16x32_bf16 v[66:69], v[180:183], v[228:231], v[66:69]
	s_barrier
	s_add_i32 s59, s59, s72
	s_mov_b64 s[90:91], s[38:39]
	s_mov_b32 m0, s59
	ds_read_b128 v[184:187], v207 offset:16384
	ds_read_b128 v[188:191], v207 offset:17408
	ds_read_b128 v[208:211], v207 offset:18432
	ds_read_b128 v[212:215], v207 offset:19456
	ds_read_b128 v[216:219], v207 offset:20480
	ds_read_b128 v[220:223], v207 offset:21504
	ds_read_b128 v[224:227], v207 offset:22528
	ds_read_b128 v[228:231], v207 offset:23552
	global_load_lds_dwordx4 v0, s[38:39]
	s_add_i32 m0, s59, 0x2000
	s_add_i32 s59, s86, s72
	global_load_lds_dwordx4 v166, s[38:39]
	s_add_u32 s38, s38, s14
	s_addc_u32 s39, s39, 0
	s_mov_b32 m0, s59
	s_nop 0
	global_load_lds_dwordx4 v0, s[38:39]
	s_add_i32 m0, s59, 0x2000
	s_nop 0
	global_load_lds_dwordx4 v166, s[38:39]
	s_mov_b32 m0, s73
	s_nop 0
	global_load_lds_dwordx4 v170, s[70:71]
	s_mov_b32 m0, s74
	s_nop 0
	global_load_lds_dwordx4 v168, s[70:71]
	s_waitcnt vmcnt(8)
	s_waitcnt lgkmcnt(0)
	s_barrier
	v_mfma_f32_16x16x32_bf16 v[62:65], v[130:133], v[184:187], v[62:65]
	v_mfma_f32_16x16x32_bf16 v[58:61], v[138:141], v[184:187], v[58:61]
	v_mfma_f32_16x16x32_bf16 v[46:49], v[130:133], v[208:211], v[46:49]
	v_mfma_f32_16x16x32_bf16 v[42:45], v[138:141], v[208:211], v[42:45]
	v_mfma_f32_16x16x32_bf16 v[30:33], v[130:133], v[216:219], v[30:33]
	v_mfma_f32_16x16x32_bf16 v[26:29], v[138:141], v[216:219], v[26:29]
	v_mfma_f32_16x16x32_bf16 v[14:17], v[130:133], v[224:227], v[14:17]
	v_mfma_f32_16x16x32_bf16 v[10:13], v[138:141], v[224:227], v[10:13]
	v_mfma_f32_16x16x32_bf16 v[62:65], v[134:137], v[188:191], v[62:65]
	v_mfma_f32_16x16x32_bf16 v[58:61], v[142:145], v[188:191], v[58:61]
	v_mfma_f32_16x16x32_bf16 v[46:49], v[134:137], v[212:215], v[46:49]
	v_mfma_f32_16x16x32_bf16 v[42:45], v[142:145], v[212:215], v[42:45]
	v_mfma_f32_16x16x32_bf16 v[30:33], v[134:137], v[220:223], v[30:33]
	v_mfma_f32_16x16x32_bf16 v[26:29], v[142:145], v[220:223], v[26:29]
	v_mfma_f32_16x16x32_bf16 v[14:17], v[134:137], v[228:231], v[14:17]
	v_mfma_f32_16x16x32_bf16 v[10:13], v[142:145], v[228:231], v[10:13]
	v_mfma_f32_16x16x32_bf16 v[54:57], v[146:149], v[184:187], v[54:57]
	v_mfma_f32_16x16x32_bf16 v[50:53], v[176:179], v[184:187], v[50:53]
	v_mfma_f32_16x16x32_bf16 v[38:41], v[146:149], v[208:211], v[38:41]
	v_mfma_f32_16x16x32_bf16 v[34:37], v[176:179], v[208:211], v[34:37]
	v_mfma_f32_16x16x32_bf16 v[22:25], v[146:149], v[216:219], v[22:25]
	v_mfma_f32_16x16x32_bf16 v[18:21], v[176:179], v[216:219], v[18:21]
	v_mfma_f32_16x16x32_bf16 v[6:9], v[146:149], v[224:227], v[6:9]
	v_mfma_f32_16x16x32_bf16 v[2:5], v[176:179], v[224:227], v[2:5]
	v_mfma_f32_16x16x32_bf16 v[54:57], v[150:153], v[188:191], v[54:57]
	v_mfma_f32_16x16x32_bf16 v[50:53], v[180:183], v[188:191], v[50:53]
	v_mfma_f32_16x16x32_bf16 v[38:41], v[150:153], v[212:215], v[38:41]
	v_mfma_f32_16x16x32_bf16 v[34:37], v[180:183], v[212:215], v[34:37]
	v_mfma_f32_16x16x32_bf16 v[22:25], v[150:153], v[220:223], v[22:25]
	v_mfma_f32_16x16x32_bf16 v[18:21], v[180:183], v[220:223], v[18:21]
	v_mfma_f32_16x16x32_bf16 v[6:9], v[150:153], v[228:231], v[6:9]
	v_mfma_f32_16x16x32_bf16 v[2:5], v[180:183], v[228:231], v[2:5]
	s_barrier
; #define PG8_STAGE(bufoff, gbase, voff) do { _Pragma("unroll") for (int _i = 0; _i < 2; ++_i) \
;         __builtin_amdgcn_global_load_lds((const unsigned*)((const char*)(gbase) + (voff)[_i]), (PG8_LAS unsigned*)(lds + (bufoff) + ldsw + _i * 8192), 16, 0, 0); } while (0)
; #define PG8_LDA(dst, b, h) do { _Pragma("unroll") for (int m = 0; m < 4; ++m) _Pragma("unroll") for (int k = 0; k < 2; ++k) dst[m][k] = *(const PG8_LAS bf16x8*)(lds + PG8_SA(b, h) + aoff + m * 2048 + k * 1024); } while (0)
; #define PG8_LDB(dst, b, h) do { _Pragma("unroll") for (int n = 0; n < 2; ++n) _Pragma("unroll") for (int k = 0; k < 2; ++k) dst[n][k] = *(const PG8_LAS bf16x8*)(lds + PG8_SB(b, h) + boff + n * 2048 + k * 1024); } while (0)
; #define PG8_MMA(ai, bj, At, Bt) do { __builtin_amdgcn_s_setprio(1); _Pragma("unroll") for (int m = 0; m < 4; ++m) _Pragma("unroll") for (int n = 0; n < 2; ++n) _Pragma("unroll") for (int k = 0; k < 2; ++k) \
;         acc[ai][bj][m][n] = __builtin_amdgcn_mfma_f32_16x16x32_bf16(Bt[n][k], At[m][k], acc[ai][bj][m][n], 0, 0, 0); __builtin_amdgcn_s_setprio(0); } while (0)
; #define PG8_WAIT_V(n) asm volatile("s_waitcnt vmcnt(" #n ")" ::: "memory")
; #define PG8_WAIT_L(n) asm volatile("s_waitcnt lgkmcnt(" #n ")" ::: "memory")
; #define PG8_BAR __builtin_amdgcn_s_barrier()
; #define PG8_SCHED __builtin_amdgcn_sched_barrier(0)
; template <class Epi, class Sched, bool ALIGN_EPI = false, bool SP2 = false>
; __device__ __forceinline__ void gemm_phase(PG8_LAS unsigned char* lds, const Gemm g, const Sched& S, const Epi& E, const int tid) {
;     ...
;             PG8_LDB(B0, 1, 0); PG8_LDB(B1, 1, 1); PG8_SCHED; PG8_LDA(At, 1, 0); PG8_STAGE(PG8_SA(0, 1), a2 + hstep, voffA);
;             PG8_WAIT_V(8); PG8_WAIT_L(0); PG8_BAR; PG8_MMA(0, 0, At, B0); PG8_MMA(0, 1, At, B1); PG8_BAR; PG8_SCHED;
;             PG8_LDA(At, 1, 1); PG8_STAGE(PG8_SB(1, 0), b3, voffB); PG8_STAGE(PG8_SB(1, 1), b3 + hstep, voffB); PG8_STAGE(PG8_SA(1, 0), a3, voffA);
;             PG8_WAIT_V(8); PG8_WAIT_L(0); PG8_BAR; PG8_MMA(1, 0, At, B0); PG8_MMA(1, 1, At, B1); PG8_BAR; PG8_SCHED;
;     ...
;         if constexpr (ALIGN_EPI) { if (wr == 0) PG8_BAR; }
	s_add_i32 s59, 0, 0x18000
	s_add_i32 s86, 0, 0x1c000
	v_add_u32_e32 v142, s59, v205
	v_add_u32_e32 v180, s86, v205
	ds_read_b128 v[130:133], v142
	ds_read_b128 v[134:137], v142 offset:1024
	ds_read_b128 v[138:141], v142 offset:2048
	ds_read_b128 v[142:145], v142 offset:3072
	ds_read_b128 v[146:149], v180
	ds_read_b128 v[150:153], v180 offset:1024
	ds_read_b128 v[176:179], v180 offset:2048
	ds_read_b128 v[180:183], v180 offset:3072
	s_add_u32 s38, s70, s14
	s_addc_u32 s39, s71, 0
	s_mov_b32 m0, s75
	ds_read_b128 v[184:187], v207 offset:32768
	ds_read_b128 v[188:191], v207 offset:33792
	ds_read_b128 v[208:211], v207 offset:34816
	ds_read_b128 v[212:215], v207 offset:35840
	ds_read_b128 v[216:219], v207 offset:36864
	ds_read_b128 v[220:223], v207 offset:37888
	ds_read_b128 v[224:227], v207 offset:38912
	ds_read_b128 v[228:231], v207 offset:39936
	global_load_lds_dwordx4 v170, s[38:39]
	s_mov_b32 m0, s76
	s_nop 0
	global_load_lds_dwordx4 v168, s[38:39]
	s_waitcnt vmcnt(8)
	s_waitcnt lgkmcnt(0)
	s_barrier
	v_mfma_f32_16x16x32_bf16 v[126:129], v[130:133], v[184:187], v[126:129]
	v_mfma_f32_16x16x32_bf16 v[122:125], v[138:141], v[184:187], v[122:125]
	v_mfma_f32_16x16x32_bf16 v[110:113], v[130:133], v[208:211], v[110:113]
	v_mfma_f32_16x16x32_bf16 v[106:109], v[138:141], v[208:211], v[106:109]
	v_mfma_f32_16x16x32_bf16 v[94:97], v[130:133], v[216:219], v[94:97]
	v_mfma_f32_16x16x32_bf16 v[90:93], v[138:141], v[216:219], v[90:93]
	v_mfma_f32_16x16x32_bf16 v[78:81], v[130:133], v[224:227], v[78:81]
	v_mfma_f32_16x16x32_bf16 v[74:77], v[138:141], v[224:227], v[74:77]
	v_mfma_f32_16x16x32_bf16 v[126:129], v[134:137], v[188:191], v[126:129]
	v_mfma_f32_16x16x32_bf16 v[122:125], v[142:145], v[188:191], v[122:125]
	v_mfma_f32_16x16x32_bf16 v[110:113], v[134:137], v[212:215], v[110:113]
	v_mfma_f32_16x16x32_bf16 v[106:109], v[142:145], v[212:215], v[106:109]
	v_mfma_f32_16x16x32_bf16 v[94:97], v[134:137], v[220:223], v[94:97]
	v_mfma_f32_16x16x32_bf16 v[90:93], v[142:145], v[220:223], v[90:93]
	v_mfma_f32_16x16x32_bf16 v[78:81], v[134:137], v[228:231], v[78:81]
	v_mfma_f32_16x16x32_bf16 v[74:77], v[142:145], v[228:231], v[74:77]
	v_mfma_f32_16x16x32_bf16 v[118:121], v[146:149], v[184:187], v[118:121]
	v_mfma_f32_16x16x32_bf16 v[114:117], v[176:179], v[184:187], v[114:117]
	v_mfma_f32_16x16x32_bf16 v[102:105], v[146:149], v[208:211], v[102:105]
	v_mfma_f32_16x16x32_bf16 v[98:101], v[176:179], v[208:211], v[98:101]
	v_mfma_f32_16x16x32_bf16 v[86:89], v[146:149], v[216:219], v[86:89]
	v_mfma_f32_16x16x32_bf16 v[82:85], v[176:179], v[216:219], v[82:85]
	v_mfma_f32_16x16x32_bf16 v[70:73], v[146:149], v[224:227], v[70:73]
	v_mfma_f32_16x16x32_bf16 v[66:69], v[176:179], v[224:227], v[66:69]
	v_mfma_f32_16x16x32_bf16 v[118:121], v[150:153], v[188:191], v[118:121]
	v_mfma_f32_16x16x32_bf16 v[114:117], v[180:183], v[188:191], v[114:117]
	v_mfma_f32_16x16x32_bf16 v[102:105], v[150:153], v[212:215], v[102:105]
	v_mfma_f32_16x16x32_bf16 v[98:101], v[180:183], v[212:215], v[98:101]
	v_mfma_f32_16x16x32_bf16 v[86:89], v[150:153], v[220:223], v[86:89]
	v_mfma_f32_16x16x32_bf16 v[82:85], v[180:183], v[220:223], v[82:85]
	v_mfma_f32_16x16x32_bf16 v[70:73], v[150:153], v[228:231], v[70:73]
	v_mfma_f32_16x16x32_bf16 v[66:69], v[180:183], v[228:231], v[66:69]
	s_barrier
	s_add_i32 s38, s59, s72
	s_add_u32 s90, s90, 0x80
	s_addc_u32 s91, s91, 0
	s_mov_b32 m0, s38
	ds_read_b128 v[184:187], v207 offset:49152
	ds_read_b128 v[188:191], v207 offset:50176
	ds_read_b128 v[208:211], v207 offset:51200
	ds_read_b128 v[212:215], v207 offset:52224
	ds_read_b128 v[216:219], v207 offset:53248
	ds_read_b128 v[220:223], v207 offset:54272
	ds_read_b128 v[224:227], v207 offset:55296
	ds_read_b128 v[228:231], v207 offset:56320
	global_load_lds_dwordx4 v0, s[90:91]
	s_add_i32 m0, s38, 0x2000
	s_add_i32 s38, s86, s72
	global_load_lds_dwordx4 v166, s[90:91]
	s_add_u32 s90, s90, s14
	s_addc_u32 s91, s91, 0
	s_mov_b32 m0, s38
	s_nop 0
	global_load_lds_dwordx4 v0, s[90:91]
	s_add_i32 m0, s38, 0x2000
	s_add_u32 s92, s70, 0x80
	s_addc_u32 s93, s71, 0
	global_load_lds_dwordx4 v166, s[90:91]
	s_mov_b32 m0, s79
	s_nop 0
	global_load_lds_dwordx4 v170, s[92:93]
	s_mov_b32 m0, s80
	s_nop 0
	global_load_lds_dwordx4 v168, s[92:93]
	s_waitcnt vmcnt(8)
	s_waitcnt lgkmcnt(0)
	s_barrier
	v_mfma_f32_16x16x32_bf16 v[62:65], v[130:133], v[184:187], v[62:65]
	v_mfma_f32_16x16x32_bf16 v[58:61], v[138:141], v[184:187], v[58:61]
	v_mfma_f32_16x16x32_bf16 v[46:49], v[130:133], v[208:211], v[46:49]
	v_mfma_f32_16x16x32_bf16 v[42:45], v[138:141], v[208:211], v[42:45]
	v_mfma_f32_16x16x32_bf16 v[30:33], v[130:133], v[216:219], v[30:33]
	v_mfma_f32_16x16x32_bf16 v[26:29], v[138:141], v[216:219], v[26:29]
	v_mfma_f32_16x16x32_bf16 v[14:17], v[130:133], v[224:227], v[14:17]
	v_mfma_f32_16x16x32_bf16 v[10:13], v[138:141], v[224:227], v[10:13]
	v_mfma_f32_16x16x32_bf16 v[62:65], v[134:137], v[188:191], v[62:65]
	v_mfma_f32_16x16x32_bf16 v[58:61], v[142:145], v[188:191], v[58:61]
	v_mfma_f32_16x16x32_bf16 v[46:49], v[134:137], v[212:215], v[46:49]
	v_mfma_f32_16x16x32_bf16 v[42:45], v[142:145], v[212:215], v[42:45]
	v_mfma_f32_16x16x32_bf16 v[30:33], v[134:137], v[220:223], v[30:33]
	v_mfma_f32_16x16x32_bf16 v[26:29], v[142:145], v[220:223], v[26:29]
	v_mfma_f32_16x16x32_bf16 v[14:17], v[134:137], v[228:231], v[14:17]
	v_mfma_f32_16x16x32_bf16 v[10:13], v[142:145], v[228:231], v[10:13]
	v_mfma_f32_16x16x32_bf16 v[54:57], v[146:149], v[184:187], v[54:57]
	v_mfma_f32_16x16x32_bf16 v[50:53], v[176:179], v[184:187], v[50:53]
	v_mfma_f32_16x16x32_bf16 v[38:41], v[146:149], v[208:211], v[38:41]
	v_mfma_f32_16x16x32_bf16 v[34:37], v[176:179], v[208:211], v[34:37]
	v_mfma_f32_16x16x32_bf16 v[22:25], v[146:149], v[216:219], v[22:25]
	v_mfma_f32_16x16x32_bf16 v[18:21], v[176:179], v[216:219], v[18:21]
	v_mfma_f32_16x16x32_bf16 v[6:9], v[146:149], v[224:227], v[6:9]
	v_mfma_f32_16x16x32_bf16 v[2:5], v[176:179], v[224:227], v[2:5]
	v_mfma_f32_16x16x32_bf16 v[54:57], v[150:153], v[188:191], v[54:57]
	v_mfma_f32_16x16x32_bf16 v[50:53], v[180:183], v[188:191], v[50:53]
	v_mfma_f32_16x16x32_bf16 v[38:41], v[150:153], v[212:215], v[38:41]
	v_mfma_f32_16x16x32_bf16 v[34:37], v[180:183], v[212:215], v[34:37]
	v_mfma_f32_16x16x32_bf16 v[22:25], v[150:153], v[220:223], v[22:25]
	v_mfma_f32_16x16x32_bf16 v[18:21], v[180:183], v[220:223], v[18:21]
	v_mfma_f32_16x16x32_bf16 v[6:9], v[150:153], v[228:231], v[6:9]
	v_mfma_f32_16x16x32_bf16 v[2:5], v[180:183], v[228:231], v[2:5]
	s_barrier
	s_add_u32 s68, s68, 0x100
	s_addc_u32 s69, s69, 0
	s_add_u32 s50, s50, 0x100
	s_addc_u32 s51, s51, 0
	s_cmp_ge_u32 s85, s78
	s_mov_b32 s70, s85
	s_cbranch_scc0 .LBB0_618
	s_and_b64 vcc, exec, s[22:23]
	s_cbranch_vccz .LBB0_621
	s_barrier
